# layer 0: part B of weight prep (w_o, w_ff1, w_ff2, bias2) also deferred to input-projection tail
# speedup vs baseline: 1.0064x; 1.0064x over previous
; #define LAS __attribute__((address_space(3)))
; #define otid() ((wv << 6) | olane())
; __device__ __forceinline__ void convert_weights(LAS unsigned char* lds, KP p, int l, int wv) {
;     unsigned char* ws = p->ws;
;     const int tid_ = otid(); const int lane = tid_ & 63, wid = tid_ >> 6;
;     LAS float* scr = (LAS float*)(lds + wid * 8704);
;     const int gw = blockIdx.x * 8 + wid, NGW = gridDim.x * 8;
;     constexpr int I_IN = 16 * (DIN / 32), I_UQ = 6 * 24, I_UKV = 4 * 32, I_BR = 8 * 32, I_O = 16 * 32, I_F1 = 16 * 128, I_F2 = 64 * 32;
;     constexpr int NIT = I_IN + I_UQ + I_UKV + 3 * I_BR + I_O + I_F1 + I_F2;
;     const int BIG = 1 << 30;
;     for (int it = gw; it < NIT; it += NGW) {
;         int r = it;
;         if (r < I_IN) { tr_item(p->w_in + (size_t)l * DM * DIN, DIN, (bf16_t*)(ws + WS_WIN), DM, 0, NGATE0, NPM - NGATE0, 1, 0, scr, r, lane); continue; } r -= I_IN;
.Lp0_full:
	s_waitcnt lgkmcnt(0)
	v_readlane_b32 s8, v255, 0
	v_readlane_b32 s9, v255, 1
	s_mov_b32 s0, s79
	s_load_dwordx2 s[10:11], s[8:9], 0xd8
	v_mbcnt_lo_u32_b32 v0, -1, 0
	v_mbcnt_hi_u32_b32 v0, -1, v0
	v_readlane_b32 s0, v255, 6
	v_or_b32_e32 v1, s82, v0
	v_ashrrev_i32_e32 v1, 6, v1
	s_mov_b32 s91, s77
	v_add_u32_e32 v18, s0, v1
	s_movk_i32 s0, 0x1460
	s_cmp_lg_u32 s90, 0
	s_cselect_b32 s0, s0, 0
	v_add_u32_e32 v18, s0, v18
	s_movk_i32 s0, 0x1460
	s_lshl_b64 s[12:13], s[90:91], 24
	s_mul_hi_u32 s28, s90, 0x20a0000
	s_mul_i32 s29, s90, 0x20a0000
	v_cmp_gt_i32_e32 vcc, s0, v18
	s_and_saveexec_b64 s[0:1], vcc
	s_cbranch_execz .LBB0_128
	s_movk_i32 s14, 0x2200
	v_bfe_u32 v19, v0, 5, 1
	v_and_b32_e32 v14, 31, v0
	v_bfe_u32 v21, v0, 3, 3
	v_lshlrev_b32_e32 v0, 3, v0
	v_mul_lo_u32 v1, v1, s14
	v_and_b32_e32 v0, 56, v0
	v_add_u32_e32 v4, 0, v1
	v_lshlrev_b32_e32 v1, 2, v14
	v_mul_u32_u24_e32 v2, 0x84, v19
	v_lshlrev_b32_e32 v192, 1, v0
	v_add3_u32 v20, v4, v1, v2
	v_mul_u32_u24_e32 v5, 0x84, v0
	s_waitcnt lgkmcnt(0)
	v_lshl_add_u64 v[0:1], s[10:11], 0, v[192:193]
	s_mov_b64 s[14:15], 0x2700000
	v_lshl_add_u64 v[2:3], v[0:1], 0, s[14:15]
	v_lshlrev_b32_e32 v6, 2, v21
	s_mov_b64 s[14:15], 0x1f00000
	v_add3_u32 v22, v4, v5, v6
	v_lshl_add_u64 v[4:5], v[0:1], 0, s[14:15]
	s_mov_b64 s[14:15], 0x1700000
	v_lshl_add_u64 v[6:7], v[0:1], 0, s[14:15]
	s_mov_b64 s[14:15], 0x1300000
	v_lshl_add_u64 v[8:9], v[0:1], 0, s[14:15]
	s_mov_b64 s[14:15], 0x1200000
	v_lshl_add_u64 v[10:11], v[0:1], 0, s[14:15]
	s_mov_b64 s[14:15], 0x1100000
	v_lshl_add_u64 v[12:13], v[0:1], 0, s[14:15]
	v_readlane_b32 s14, v255, 29
	v_readlane_b32 s15, v255, 30
	v_mov_b32_e32 v15, 0x1c340
	s_lshl_b64 s[2:3], s[90:91], 22
	s_lshl_b64 s[4:5], s[90:91], 23
	s_lshl_b64 s[6:7], s[90:91], 20
	v_or_b32_e32 v23, 8, v21
	v_or_b32_e32 v24, 16, v21
	v_or_b32_e32 v25, 24, v21
	v_lshlrev_b32_e32 v26, 5, v18
	s_lshl_b32 s30, s14, 5
	v_lshl_add_u32 v27, v18, 1, v15
	s_lshl_b32 s31, s14, 1
	s_mov_b64 s[14:15], 0
	v_lshlrev_b32_e32 v14, 2, v14
	v_add_u32_e32 v28, 0x400, v20
	v_add_u32_e32 v29, 0x800, v20
	v_add_u32_e32 v30, 0xc00, v20
	v_add_u32_e32 v31, 0x1000, v20
	v_add_u32_e32 v32, 0x1400, v20
	v_add_u32_e32 v33, 0x1800, v20
	v_add_u32_e32 v34, 0x1c00, v20
	s_branch .LBB0_100

; #define LAS __attribute__((address_space(3)))
; __device__ __forceinline__ void bias_gemv(LAS unsigned char* lds, KP p, int l, int wv) {
;     ...
;     constexpr int IT1 = (DIN + 63) / 64, IT2 = DFF / 64;
;     for (int it = blockIdx.x; it < IT1 + IT2; it += gridDim.x) {
;         const bool second = it >= IT1; const int n0 = (second ? it - IT1 : it) * 64; const int N = second ? DFF : DIN;
;         const int col = n0 + lane; const bool on = col < N;
;         const float* W = (second ? p->w_ff1 + (size_t)l * DM * DFF : p->w_in + (size_t)l * DM * DIN) + (on ? col : 0);
;         const LAS float* s9 = sv + (second ? 9216 : 0);
.LBB0_158:
	s_or_b64 exec, exec, s[0:1]
	v_readlane_b32 s0, v255, 10
	v_readlane_b32 s1, v255, 11
	s_cmpk_lt_i32 s79, 0x83
	s_cselect_b64 s[2:3], -1, 0
	s_cmp_lg_u32 s90, -1
	s_cselect_b64 s[0:1], s[2:3], s[0:1]
	s_andn2_b64 vcc, exec, s[0:1]
	s_waitcnt lgkmcnt(0)
	s_barrier
	s_cbranch_vccnz .LBB0_171
	v_and_b32_e32 v1, 63, v4
	s_add_i32 s0, 0, 0x12000
	v_lshl_add_u32 v25, v1, 2, s0
	s_movk_i32 s0, 0x240
	v_ashrrev_i32_e32 v3, 6, v0
	v_cmp_gt_i32_e64 s[2:3], s0, v0
	s_add_u32 s0, s10, 0x3180000
	v_lshlrev_b32_e32 v2, 7, v3
	s_addc_u32 s1, s11, 0
	s_movk_i32 s4, 0x900
	s_add_u32 s6, s10, 0x31d0000
	v_mul_lo_u32 v4, v3, s4
	v_lshl_add_u32 v31, v3, 9, 0
	v_ashrrev_i32_e32 v3, 31, v2
	s_addc_u32 s7, s11, 0
	v_or_b32_e32 v27, 0x78, v2
	v_add_u32_e32 v29, -8, v2
	v_lshlrev_b64 v[2:3], 2, v[2:3]
	v_add_u32_e32 v32, v25, v4
	s_movk_i32 s24, 0x83
	s_cmp_lg_u32 s90, 0
	s_cselect_b32 s24, s24, 0
	s_add_i32 s24, s24, s79
	s_branch .LBB0_161

; #define LAS __attribute__((address_space(3)))
; #define otid() ((wv << 6) | olane())
; __device__ __forceinline__ void convert_weights(LAS unsigned char* lds, KP p, int l, int wv) {
;     unsigned char* ws = p->ws;
;     const int tid_ = otid(); const int lane = tid_ & 63, wid = tid_ >> 6;
;     LAS float* scr = (LAS float*)(lds + wid * 8704);
;     const int gw = blockIdx.x * 8 + wid, NGW = gridDim.x * 8;
;     constexpr int I_IN = 16 * (DIN / 32), I_UQ = 6 * 24, I_UKV = 4 * 32, I_BR = 8 * 32, I_O = 16 * 32, I_F1 = 16 * 128, I_F2 = 64 * 32;
;     constexpr int NIT = I_IN + I_UQ + I_UKV + 3 * I_BR + I_O + I_F1 + I_F2;
;     const int BIG = 1 << 30;
;     for (int it = gw; it < NIT; it += NGW) {
;         int r = it;
;         if (r < I_IN) { tr_item(p->w_in + (size_t)l * DM * DIN, DIN, (bf16_t*)(ws + WS_WIN), DM, 0, NGATE0, NPM - NGATE0, 1, 0, scr, r, lane); continue; } r -= I_IN;
.LBB0_317:
	s_cmp_lt_u32 s79, 0x48
	s_cbranch_scc1 .Lp0b_skip
	v_readlane_b32 s0, v255, 6
	v_readlane_b32 s1, v255, 7
	v_readlane_b32 s2, v255, 23
	v_readlane_b32 s3, v255, 24
	v_readlane_b32 s4, v255, 25
	v_readlane_b32 s5, v255, 26
	v_readlane_b32 s6, v255, 29
	v_readlane_b32 s7, v255, 30
	s_nop 3
	v_writelane_b32 v255, s60, 49
	v_writelane_b32 v255, s66, 50
	v_writelane_b32 v255, s0, 51
	v_writelane_b32 v255, s1, 52
	v_writelane_b32 v255, s2, 53
	v_writelane_b32 v255, s3, 54
	v_writelane_b32 v255, s4, 55
	v_writelane_b32 v255, s5, 56
	v_writelane_b32 v255, s6, 57
	v_writelane_b32 v255, s7, 58
	s_sub_i32 s79, s79, 0x48
	s_movk_i32 s60, 0xb8
	s_mov_b32 s66, 0x17000
	s_movk_i32 s89, 0x47ff
	s_lshl_b32 s0, s79, 3
	s_lshl_b32 s1, s79, 9
	s_mov_b32 s2, 0x170000
	s_mov_b32 s3, 0
	s_mov_b32 s4, 0x5c0000
	s_movk_i32 s6, 0x5c0
	v_writelane_b32 v255, s0, 6
	v_writelane_b32 v255, s1, 7
	v_writelane_b32 v255, s2, 23
	v_writelane_b32 v255, s3, 24
	v_writelane_b32 v255, s4, 25
	v_writelane_b32 v255, s3, 26
	v_writelane_b32 v255, s6, 29
	v_writelane_b32 v255, s3, 30
.Lb_top:
	s_waitcnt lgkmcnt(0)
	v_readlane_b32 s8, v255, 0
	v_readlane_b32 s9, v255, 1
	s_mov_b32 s0, s79
	s_load_dwordx2 s[10:11], s[8:9], 0xd8
	v_mbcnt_lo_u32_b32 v0, -1, 0
	v_mbcnt_hi_u32_b32 v0, -1, v0
	v_readlane_b32 s0, v255, 6
	v_or_b32_e32 v1, s82, v0
	v_ashrrev_i32_e32 v1, 6, v1
	s_mov_b32 s91, s77
	v_add_u32_e32 v18, s0, v1
	s_movk_i32 s0, 0x1460
	s_cmp_lg_u32 s90, -1
	s_cselect_b32 s0, s0, 0
	v_add_u32_e32 v18, s0, v18
	s_movk_i32 s0, 0x2660
	s_lshl_b64 s[12:13], s[90:91], 24
	s_mul_hi_u32 s28, s90, 0x20a0000
	s_mul_i32 s29, s90, 0x20a0000
	v_cmp_gt_i32_e32 vcc, s0, v18
	s_and_saveexec_b64 s[0:1], vcc
	s_cbranch_execz .Lb_128
	s_movk_i32 s14, 0x2200
	v_bfe_u32 v19, v0, 5, 1
	v_and_b32_e32 v14, 31, v0
	v_bfe_u32 v21, v0, 3, 3
	v_lshlrev_b32_e32 v0, 3, v0
	v_mul_lo_u32 v1, v1, s14
	v_and_b32_e32 v0, 56, v0
	v_add_u32_e32 v4, 0, v1
	v_lshlrev_b32_e32 v1, 2, v14
	v_mul_u32_u24_e32 v2, 0x84, v19
	v_lshlrev_b32_e32 v192, 1, v0
	v_add3_u32 v20, v4, v1, v2
	v_mul_u32_u24_e32 v5, 0x84, v0
	s_waitcnt lgkmcnt(0)
	v_lshl_add_u64 v[0:1], s[10:11], 0, v[192:193]
	s_mov_b64 s[14:15], 0x2700000
	v_lshl_add_u64 v[2:3], v[0:1], 0, s[14:15]
	v_lshlrev_b32_e32 v6, 2, v21
	s_mov_b64 s[14:15], 0x1f00000
	v_add3_u32 v22, v4, v5, v6
	v_lshl_add_u64 v[4:5], v[0:1], 0, s[14:15]
	s_mov_b64 s[14:15], 0x1700000
	v_lshl_add_u64 v[6:7], v[0:1], 0, s[14:15]
	s_mov_b64 s[14:15], 0x1300000
	v_lshl_add_u64 v[8:9], v[0:1], 0, s[14:15]
	s_mov_b64 s[14:15], 0x1200000
	v_lshl_add_u64 v[10:11], v[0:1], 0, s[14:15]
	s_mov_b64 s[14:15], 0x1100000
	v_lshl_add_u64 v[12:13], v[0:1], 0, s[14:15]
	v_readlane_b32 s14, v255, 29
	v_readlane_b32 s15, v255, 30
	v_mov_b32_e32 v15, 0x1c340
	s_lshl_b64 s[2:3], s[90:91], 22
	s_lshl_b64 s[4:5], s[90:91], 23
	s_lshl_b64 s[6:7], s[90:91], 20
	v_or_b32_e32 v23, 8, v21
	v_or_b32_e32 v24, 16, v21
	v_or_b32_e32 v25, 24, v21
	v_lshlrev_b32_e32 v26, 5, v18
	s_lshl_b32 s30, s14, 5
	v_lshl_add_u32 v27, v18, 1, v15
	s_lshl_b32 s31, s14, 1
	s_mov_b64 s[14:15], 0
	v_lshlrev_b32_e32 v14, 2, v14
	v_add_u32_e32 v28, 0x400, v20
	v_add_u32_e32 v29, 0x800, v20
	v_add_u32_e32 v30, 0xc00, v20
	v_add_u32_e32 v31, 0x1000, v20
	v_add_u32_e32 v32, 0x1400, v20
	v_add_u32_e32 v33, 0x1800, v20
	v_add_u32_e32 v34, 0x1c00, v20
	s_branch .Lb_100

; #define otid() ((wv << 6) | olane())
; __device__ __forceinline__ void convert_weights(LAS unsigned char* lds, KP p, int l, int wv) {
;     ...
;     { const int gt = blockIdx.x * 512 + otid(), NT = gridDim.x * 512; u32x4* z = (u32x4*)((bf16_t*)(ws + WS_WIN) + (size_t)NGATE0 * DM);
;       unsigned z0 = 0u; asm volatile("" : "+v"(z0));
;       for (int i = gt; i < (NPM - NGATE0) * DM / 8; i += NT) z[i] = (u32x4){z0, z0, z0, z0}; }
.Lb_128:
	s_or_b64 exec, exec, s[0:1]
	s_cmp_lg_u32 s90, -1
	s_cbranch_scc1 .Lb_146
	v_mbcnt_lo_u32_b32 v0, -1, 0
	v_mbcnt_hi_u32_b32 v0, -1, v0
	v_readlane_b32 s0, v255, 7
	v_or_b32_e32 v0, s67, v0
	s_nop 0
	v_add_u32_e32 v4, s0, v0
	s_movk_i32 s0, 0x3000
	v_mov_b32_e32 v0, v193
	v_cmp_gt_i32_e32 vcc, s0, v4
	s_and_saveexec_b64 s[0:1], vcc
	v_readlane_b32 s6, v255, 23
	v_readlane_b32 s7, v255, 24
	s_cbranch_execz .Lb_131
	v_ashrrev_i32_e32 v5, 31, v4
	s_waitcnt lgkmcnt(0)
	v_lshl_add_u64 v[6:7], v[4:5], 4, s[10:11]
	s_mov_b64 s[2:3], 0x850000
	v_mov_b32_e32 v1, v0
	v_mov_b32_e32 v2, v0
	v_mov_b32_e32 v3, v0
	v_lshl_add_u64 v[6:7], v[6:7], 0, s[2:3]
	s_mov_b64 s[2:3], 0

; #define LAS __attribute__((address_space(3)))
; __device__ __forceinline__ void bias_gemv(LAS unsigned char* lds, KP p, int l, int wv) {
;     ...
;     constexpr int IT1 = (DIN + 63) / 64, IT2 = DFF / 64;
;     for (int it = blockIdx.x; it < IT1 + IT2; it += gridDim.x) {
;         const bool second = it >= IT1; const int n0 = (second ? it - IT1 : it) * 64; const int N = second ? DFF : DIN;
;         const int col = n0 + lane; const bool on = col < N;
;         const float* W = (second ? p->w_ff1 + (size_t)l * DM * DFF : p->w_in + (size_t)l * DM * DIN) + (on ? col : 0);
;         const LAS float* s9 = sv + (second ? 9216 : 0);
.Lb_158:
	s_or_b64 exec, exec, s[0:1]
	v_readlane_b32 s0, v255, 10
	v_readlane_b32 s1, v255, 11
	s_cmpk_lt_i32 s79, 64
	s_cselect_b64 s[2:3], -1, 0
	s_cmp_lg_u32 s90, -1
	s_cselect_b64 s[0:1], s[2:3], s[0:1]
	s_andn2_b64 vcc, exec, s[0:1]
	s_waitcnt lgkmcnt(0)
	s_barrier
	s_cbranch_vccnz .Lb_171
	v_and_b32_e32 v1, 63, v4
	s_add_i32 s0, 0, 0x12000
	v_lshl_add_u32 v25, v1, 2, s0
	s_movk_i32 s0, 0x240
	v_ashrrev_i32_e32 v3, 6, v0
	v_cmp_gt_i32_e64 s[2:3], s0, v0
	s_add_u32 s0, s10, 0x3180000
	v_lshlrev_b32_e32 v2, 7, v3
	s_addc_u32 s1, s11, 0
	s_movk_i32 s4, 0x900
	s_add_u32 s6, s10, 0x31d0000
	v_mul_lo_u32 v4, v3, s4
	v_lshl_add_u32 v31, v3, 9, 0
	v_ashrrev_i32_e32 v3, 31, v2
	s_addc_u32 s7, s11, 0
	v_or_b32_e32 v27, 0x78, v2
	v_add_u32_e32 v29, -8, v2
	v_lshlrev_b64 v[2:3], 2, v[2:3]
	v_add_u32_e32 v32, v25, v4
	s_movk_i32 s24, 0x83
	s_cmp_lg_u32 s90, -1
	s_cselect_b32 s24, s24, 0
	s_add_i32 s24, s24, s79
	s_branch .Lb_161

; __device__ __forceinline__ u32x2 pack4(f32x4 v) { u32x2 w; w.x = cvtpk(v[0], v[1]); w.y = cvtpk(v[2], v[3]); return w; }
; #define otid() ((wv << 6) | olane())
; __device__ __forceinline__ void init_h(KP p, int wv) {
;     const int tid_ = otid(); const int lane = tid_ & 63, wid = tid_ >> 6;
;     const int gw = blockIdx.x * 8 + wid, NGW = gridDim.x * 8;
;     const float* vm = (const float*)(p->ws + WS_VM);
;     bf16_t* H = (bf16_t*)(p->ws + WS_H); float* part = (float*)(p->ws + WS_PART);
;     for (int row = gw; row < MT; row += NGW) {
;         const float* xr = row < MX ? p->x + (size_t)row * DM : p->ctx + (size_t)(row - MX) * DM;
;         const float* vr = vm + (size_t)(row < MX ? (row >> 11) : 8) * DM;
;         float s = 0.f;
; #pragma unroll
;         for (int j = 0; j < 4; ++j) { const int col = 4 * lane + 256 * j; const f32x4 v = *(const f32x4*)(xr + col); s += (v[0] * v[0] + v[1] * v[1]) + (v[2] * v[2] + v[3] * v[3]);
;             *(u32x2*)(H + (size_t)row * DM + col) = pack4(v * *(const f32x4*)(vr + col)); }
;         s = wave_sum(s);
;         if (lane < 16) part[(size_t)row * 16 + lane] = lane == 0 ? s : 0.f;
;     }
.Lb_171:
	s_cmp_eq_u32 s90, 0
	s_cselect_b64 s[0:1], -1, 0
	v_writelane_b32 v255, s0, 41
	s_cmp_lg_u32 s90, -1
	s_nop 0
	v_writelane_b32 v255, s1, 42
	s_cbranch_scc1 .Lb_exit
	v_mbcnt_lo_u32_b32 v1, -1, 0
	v_mbcnt_hi_u32_b32 v1, -1, v1
	v_readlane_b32 s0, v255, 6
	v_or_b32_e32 v0, s82, v1
	v_ashrrev_i32_e32 v0, 6, v0
	v_add_u32_e32 v0, s0, v0
	s_movk_i32 s0, 0x4800
	v_cmp_gt_i32_e32 vcc, s0, v0
	s_and_saveexec_b64 s[0:1], vcc
	s_cbranch_execz .Lb_181
	v_and_b32_e32 v1, 63, v1
	v_lshlrev_b32_e32 v192, 2, v1
	v_lshlrev_b32_e32 v4, 4, v1
	v_mov_b32_e32 v5, v193
	v_lshl_add_u64 v[2:3], s[10:11], 0, v[192:193]
	s_mov_b64 s[2:3], 0x1fa00000
	v_lshl_add_u64 v[4:5], s[10:11], 0, v[4:5]
	s_mov_b64 s[4:5], 0x3101000
	v_lshlrev_b32_e32 v6, 3, v1
	v_mov_b32_e32 v7, v193
	v_cmp_gt_u32_e32 vcc, 16, v1
	v_lshl_add_u64 v[2:3], v[2:3], 0, s[2:3]
	v_cmp_eq_u32_e64 s[2:3], 0, v1
	v_lshl_add_u64 v[4:5], v[4:5], 0, s[4:5]
	v_lshl_add_u64 v[6:7], s[10:11], 0, v[6:7]
	s_mov_b64 s[4:5], 0x3c00000
	v_ashrrev_i32_e32 v1, 31, v0
	v_lshl_add_u64 v[6:7], v[6:7], 0, s[4:5]
	v_lshlrev_b64 v[8:9], 12, v[0:1]
	s_mov_b64 s[6:7], 0
	v_lshlrev_b32_e32 v192, 2, v192
	s_branch .Lb_175
